# prompt forgetting-attention fast loop rewritten by hand: software-pipelined (QK of next tile and PV interleaved with softmax VALU), joint row max per 64-key tile, 3 LDS stages
# speedup vs baseline: 1.0518x; 1.0456x over previous
; #define LDS_AS __attribute__((address_space(3)))
; template <int MODE>
; DI void prompt_unit(const Params& p, int b, int h, int qt, char* smem) {
;     int tid_ = threadIdx.x; asm volatile("" : "+v"(tid_));
;     const int tid = tid_, lane = tid & 63, wave = tid >> 6, l31 = lane & 31, hh = lane >> 5;
;     LDS_AS char* lb = (LDS_AS char*)smem;
;     const int t0 = qt * 256, wq0 = t0 + 32 * wave;
;     const int qpos = wq0 + l31;
;     const bool wave_valid = wq0 < LP;
;     const int qcol = (MODE == 0 ? 0 : 2048) + h * 64, kcol = qcol + 512, vcol = qcol + 1024, gcol = qcol + 1536;
;     const size_t rowb = (size_t)b * LPAD;
;     bf16x8 q[4];
;     {
;         const int qr = qpos < LPAD ? qpos : LPAD - 1;
;         const bf16_t* qp = p.u + (rowb + qr) * NU + qcol + 8 * hh;
; #pragma unroll
;         for (int s = 0; s < 4; ++s) q[s] = *(const bf16x8*)(qp + 16 * s);
;     }
;     AttnState st;
; #pragma unroll
;     for (int i = 0; i < 16; ++i) { st.o0[i] = 0.f; st.o1[i] = 0.f; }
;     st.m = -1e30f; st.l = 0.f;
;     const int kt_max = (4 * qt + 3) < 64 ? (4 * qt + 3) : 64;
;     const float* cb = p.c2p + (size_t)(b * 8 + h) * LPAD;
;     float cref = 0.f;
;     if (MODE == 1) cref = cb[t0 < LP ? t0 : LP - 1];
;     u32x4 rk, rv; float rbias = 0.f;
;     const int r0 = tid >> 3, c0 = tid & 7;
;     auto pload = [&](int kt) {
;         const bf16_t* kb = p.u + (rowb + (size_t)kt * 64 + r0) * NU + c0 * 8;
;         rk = *(const u32x4*)(kb + kcol); rv = *(const u32x4*)(kb + vcol);
;         if (MODE == 1 && tid < 64) rbias = cref - cb[kt * 64 + tid];
;     };
;     auto pstore = [&](int sg) {
;         LDS_AS char* base = lb + sg * PSTG + r0 * 144 + c0 * 16;
;         *(LDS_AS u32x4*)(base) = rk; *(LDS_AS u32x4*)(base + 9216) = rv;
;         if (MODE == 1 && tid < 64) *(LDS_AS float*)(lb + sg * PSTG + 18432 + tid * 4) = rbias;
;     };
;     __syncthreads();
;     pload(kt_max); pstore(0);
;     __syncthreads();
;     int stg = 0;
.LBB0_513:
	s_or_b64 exec, exec, s[0:1]
	v_mov_b32_e32 v0, s63
	s_waitcnt lgkmcnt(0)
	s_barrier
	ds_read_b32 v0, v0
	s_mov_b64 s[0:1], -1
	s_waitcnt lgkmcnt(0)
	v_cmp_lt_i32_e32 vcc, s66, v0
	v_readfirstlane_b32 s4, v0
	s_cbranch_vccnz .LBB0_508
	s_ashr_i32 s1, s4, 5
	v_mov_b32_e32 v4, v138
	s_sub_i32 s1, 16, s1
	s_lshl_b32 s100, s1, 2
	s_add_i32 s100, s100, -2
	s_lshl_b32 s5, s1, 8
	v_ashrrev_i32_e32 v0, 1, v4
	v_and_b32_e32 v0, 0xffffffe0, v0
	v_and_b32_e32 v5, 31, v4
	s_waitcnt vmcnt(1)
	v_add_u32_e32 v89, s5, v0
	v_or_b32_e32 v88, v89, v5
	s_bfe_u32 s0, s4, 0x20003
	v_min_i32_e32 v0, 0x103f, v88
	s_mul_i32 s8, s0, 0x1040
	s_mov_b32 s9, s11
	v_ashrrev_i32_e32 v1, 31, v0
	s_lshl_b32 s6, s4, 6
	v_lshl_add_u64 v[0:1], v[0:1], 0, s[8:9]
	s_and_b32 s10, s6, 0x1c0
	v_lshlrev_b64 v[0:1], 13, v[0:1]
	v_lshl_add_u64 v[0:1], s[68:69], 0, v[0:1]
	s_lshl_b32 s6, s10, 1
	s_mov_b32 s7, s11
	s_lshl_b32 s0, s1, 2
	s_or_b32 s34, s10, 0xa00
	v_lshl_add_u64 v[0:1], v[0:1], 0, s[6:7]
	s_or_b32 s7, s10, 0xc00
	s_or_b32 s0, s0, 3
	s_cmp_lt_u32 s1, 16
	v_bfe_u32 v6, v4, 5, 1
	s_cselect_b32 s10, s0, 64
	s_and_b32 s0, s4, 31
	v_lshlrev_b32_e32 v130, 4, v6
	s_mulk_i32 s0, 0x4100
	v_lshl_add_u64 v[0:1], v[0:1], 0, v[130:131]
	s_add_u32 s30, s72, s0
	v_lshl_add_u64 v[2:3], v[0:1], 0, s[22:23]
	v_add_co_u32_e32 v0, vcc, s67, v0
	s_addc_u32 s31, s73, 0
	s_min_u32 s0, s5, 0x100f
	v_addc_co_u32_e32 v1, vcc, 0, v1, vcc
	global_load_dwordx4 v[64:67], v[2:3], off offset:32
	global_load_dwordx4 v[68:71], v[2:3], off offset:64
	global_load_dwordx4 v[72:75], v[0:1], off
	global_load_dwordx4 v[76:79], v[2:3], off offset:96
	s_lshl_b32 s0, s0, 2
	v_ashrrev_i32_e32 v2, 3, v4
	v_mov_b32_e32 v0, s0
	v_ashrrev_i32_e32 v3, 31, v2
	s_lshl_b64 s[0:1], s[10:11], 19
	global_load_dword v95, v0, s[30:31]
	v_lshl_add_u64 v[0:1], v[2:3], 0, s[8:9]
	s_add_u32 s0, s68, s0
	v_and_b32_e32 v7, 7, v4
	v_lshlrev_b64 v[0:1], 13, v[0:1]
	s_addc_u32 s1, s69, s1
	v_lshl_add_u64 v[8:9], s[0:1], 0, v[0:1]
	v_lshlrev_b32_e32 v90, 4, v7
	v_mov_b32_e32 v91, v131
	v_lshl_add_u64 v[8:9], v[8:9], 0, v[90:91]
	s_lshl_b32 s34, s34, 1
	s_mov_b32 s35, s11
	v_lshl_add_u64 v[10:11], v[8:9], 0, s[34:35]
	s_lshl_b32 s36, s7, 1
	s_mov_b32 s37, s11
	s_barrier
	v_lshl_add_u64 v[8:9], v[8:9], 0, s[36:37]
	global_load_dwordx4 v[80:83], v[10:11], off
	global_load_dwordx4 v[84:87], v[8:9], off
	v_cmp_gt_i32_e64 s[0:1], 64, v4
	v_mov_b32_e32 v97, 0
	s_and_saveexec_b64 s[4:5], s[0:1]
	s_cbranch_execz .LBB0_516
	v_lshl_add_u32 v8, s10, 6, v4
	v_ashrrev_i32_e32 v9, 31, v8
	v_lshl_add_u64 v[8:9], v[8:9], 2, s[30:31]
	global_load_dword v3, v[8:9], off
	s_waitcnt vmcnt(0)
	v_sub_f32_e32 v97, v95, v3

; #define LDS_AS __attribute__((address_space(3)))
; template <int MODE>
; DI void prompt_unit(const Params& p, int b, int h, int qt, char* smem) {
;     ...
;     auto pstore = [&](int sg) {
;         LDS_AS char* base = lb + sg * PSTG + r0 * 144 + c0 * 16;
;         *(LDS_AS u32x4*)(base) = rk; *(LDS_AS u32x4*)(base + 9216) = rv;
;         if (MODE == 1 && tid < 64) *(LDS_AS float*)(lb + sg * PSTG + 18432 + tid * 4) = rbias;
;     };
;     ...
;         if (kt > 0) pload(kt - 1);
;         if (!wdone) {
;             LDS_AS const char* sb = lb + stg * PSTG;
;             if (MODE == 1 && kt * 64 + 63 < wq0) attn_tile64_fox(sb, sb + 9216, sb + 18432, q, st, lane);
;             else
; #pragma unroll
;     ...
;                 const int kp0 = kt * 64 + sub * 32;
;                 if (kp0 <= wq0 + 31) {
;                     const bool nm = (kp0 + 31 >= wq0);
;                     attn_subtile<MODE>(sb + sub * 32 * 144, sb + 9216 + sub * 32 * 144, sb + 18432 + sub * 128, q, st, kp0, qpos, nm, lane);
;                 }
;             }
;             if (MODE == 0) wdone = __all(st.l < -SB_THRESH);
;         }
;         if (kt > 0) pstore(stg ^ 1);
;         if (MODE == 0) { if (__syncthreads_and(wdone ? 1 : 0)) break; }
;         else __syncthreads();
;         stg ^= 1;
.LBB0_520:
	s_add_i32 s101, s100, 1
	s_cmp_lg_u32 s10, s101
	s_cbranch_scc1 .Lfoxp_noxs
	s_cmp_eq_u32 s100, -2
	s_cbranch_scc1 .Lfoxp_noxs
	s_waitcnt vmcnt(0)
	s_mov_b32 s101, 0x9300
	v_add3_u32 v164, s101, v98, v90
	ds_write_b128 v164, v[148:151]
	ds_write_b128 v164, v[152:155] offset:9216
	s_and_saveexec_b64 s[42:43], s[0:1]
	s_cbranch_execz .Lfoxp_xs1
	v_sub_f32_e32 v156, v95, v156
	v_add_u32_e32 v164, s101, v99
	ds_write_b32 v164, v156 offset:18432

; #define LDS_AS __attribute__((address_space(3)))
; template <int MODE>
; DI void prompt_unit(const Params& p, int b, int h, int qt, char* smem) {
;     ...
;         if (kt > 0) pload(kt - 1);
;         if (!wdone) {
;             LDS_AS const char* sb = lb + stg * PSTG;
;             if (MODE == 1 && kt * 64 + 63 < wq0) attn_tile64_fox(sb, sb + 9216, sb + 18432, q, st, lane);
;             else
; #pragma unroll
;     ...
;                 const int kp0 = kt * 64 + sub * 32;
;                 if (kp0 <= wq0 + 31) {
;                     const bool nm = (kp0 + 31 >= wq0);
;                     attn_subtile<MODE>(sb + sub * 32 * 144, sb + 9216 + sub * 32 * 144, sb + 18432 + sub * 128, q, st, kp0, qpos, nm, lane);
;                 }
;             }
;             if (MODE == 0) wdone = __all(st.l < -SB_THRESH);
;         }
;         if (kt > 0) pstore(stg ^ 1);
;         if (MODE == 0) { if (__syncthreads_and(wdone ? 1 : 0)) break; }
;         else __syncthreads();
;         stg ^= 1;
;     }
.Lfoxp_noxs:
	s_sub_i32 s7, s7, 64
	s_add_i32 s10, s10, -1
	s_cmp_eq_u32 s10, s100
	s_waitcnt lgkmcnt(0)
	s_barrier
	s_cbranch_scc1 .Lfoxp_entry

; template <int MODE>
; DI void prompt_unit(const Params& p, int b, int h, int qt, char* smem) {
;     ...
;     auto pload = [&](int kt) {
;         const bf16_t* kb = p.u + (rowb + (size_t)kt * 64 + r0) * NU + c0 * 8;
;         rk = *(const u32x4*)(kb + kcol); rv = *(const u32x4*)(kb + vcol);
;         if (MODE == 1 && tid < 64) rbias = cref - cb[kt * 64 + tid];
;     };
;     ...
;         if (kt > 0) pload(kt - 1);
.LBB0_525:
	s_add_i32 s101, s100, 1
	s_cmp_lg_u32 s10, s101
	s_cbranch_scc1 .Lfoxp_noxl
	s_cmp_eq_u32 s100, -2
	s_cbranch_scc1 .Lfoxp_noxl
	s_mov_b32 s42, s100
	s_mov_b32 s43, 0
	s_lshl_b64 s[42:43], s[42:43], 19
	v_lshl_add_u64 v[160:161], v[92:93], 0, s[42:43]
	s_mov_b32 s35, 0
	s_mov_b32 s37, 0
	v_lshl_add_u64 v[162:163], v[160:161], 0, s[34:35]
	v_lshl_add_u64 v[160:161], v[160:161], 0, s[36:37]
	global_load_dwordx4 v[148:151], v[162:163], off
	global_load_dwordx4 v[152:155], v[160:161], off
	s_and_saveexec_b64 s[42:43], s[0:1]
	s_cbranch_execz .Lfoxp_xl1
	v_lshl_add_u32 v164, s100, 6, v138
	v_lshlrev_b32_e32 v164, 2, v164
	global_load_dword v156, v164, s[30:31]

; #define LDS_AS __attribute__((address_space(3)))
; DI void fox_softmax32(f32x16& s, AttnState& st, bf16x8 (&pf)[2]) {
;     float mx = max2f(s[0], s[1]);
; #pragma unroll
;     for (int i = 2; i < 16; i += 2) mx = max3f(mx, s[i], s[i + 1]);
;     mx = max2f(mx, __shfl_xor(mx, 32));
;     const float mn = max2f(st.m, mx);
;     if (__any(mn > st.m)) { const float a = __builtin_amdgcn_exp2f(st.m - mn); st.o0 = st.o0 * a; st.o1 = st.o1 * a; st.l *= a; }
;     st.m = mn;
;     const f32x2 mn2 = {mn, mn};
;     f32x2 acc2 = {0.f, 0.f};
; #pragma unroll
;     for (int i = 0; i < 16; i += 2) {
;         f32x2 t = {s[i], s[i + 1]};
;         t = t - mn2;
;         t[0] = __builtin_amdgcn_exp2f(t[0]); t[1] = __builtin_amdgcn_exp2f(t[1]);
;         acc2 = acc2 + t;
;         s[i] = t[0]; s[i + 1] = t[1];
;     }
;     st.l += acc2[0] + acc2[1];
; #pragma unroll
;     for (int s2 = 0; s2 < 2; ++s2) {
;         u32x4 w;
; DI void attn_tile64_fox(LDS_AS const char* Kl, LDS_AS const char* Vl, LDS_AS const char* biasl, const bf16x8 (&q)[4], AttnState& st, int lane) {
;     const int l31 = lane & 31, hh = lane >> 5;
;     f32x16 s0, s1;
; #pragma unroll
;     for (int g = 0; g < 4; ++g) {
;         const f32x4 b0 = *(LDS_AS const f32x4*)(biasl + (8 * g + 4 * hh) * 4);
;         const f32x4 b1 = *(LDS_AS const f32x4*)(biasl + 128 + (8 * g + 4 * hh) * 4);
;         s0[4 * g] = b0[0]; s0[4 * g + 1] = b0[1]; s0[4 * g + 2] = b0[2]; s0[4 * g + 3] = b0[3];
;         s1[4 * g] = b1[0]; s1[4 * g + 1] = b1[1]; s1[4 * g + 2] = b1[2]; s1[4 * g + 3] = b1[3];
;     }
;     bf16x8 k0[4], k1[4];
; #pragma unroll
;     for (int stp = 0; stp < 4; ++stp) {
;         k1[stp] = *(LDS_AS const bf16x8*)(Kl + 32 * 144 + l31 * 144 + (2 * stp + hh) * 16);
;         k0[stp] = *(LDS_AS const bf16x8*)(Kl + l31 * 144 + (2 * stp + hh) * 16);
;     }
; #pragma unroll
;     for (int stp = 0; stp < 4; ++stp) s1 = MFMA(k1[stp], q[stp], s1);
; #pragma unroll
;     for (int stp = 0; stp < 4; ++stp) s0 = MFMA(k0[stp], q[stp], s0);
;     __builtin_amdgcn_sched_barrier(0);
;     bf16x8 pf1[2], pf0[2];
;     fox_softmax32(s1, st, pf1);
;     __builtin_amdgcn_sched_barrier(0);
;     fox_pv32(Vl + 32 * 144, pf1, st, lane);
;     __builtin_amdgcn_sched_barrier(0);
;     fox_softmax32(s0, st, pf0);
;     __builtin_amdgcn_sched_barrier(0);
;     fox_pv32(Vl, pf0, st, lane);
; }
.Lfoxp_entry:
	s_cmp_eq_u32 s100, -2
	s_cbranch_scc1 .LBB0_548
	s_mul_i32 s38, s98, 0x4900
	s_addk_i32 s38, 0x100
	s_mov_b32 s39, 0x9300
	s_xor_b32 s46, s98, 1
	s_mul_i32 s46, s46, 0x4900
	s_addk_i32 s46, 0x100
	s_add_i32 s10, s100, 1
	s_mov_b32 s35, 0
	s_mov_b32 s37, 0
	v_add_u32_e32 v157, v104, v101
	v_add_u32_e32 v158, v105, v103
	v_add_u32_e32 v159, v98, v90
	v_xor_b32_e32 v112, 32, v174
	v_lshlrev_b32_e32 v112, 2, v112
	v_mov_b32_e32 v108, v107
	v_mov_b32_e32 v109, 0
	v_mov_b32_e32 v110, 0
	v_mov_b32_e32 v111, 0
	s_and_b64 vcc, exec, s[4:5]
	s_cbranch_vccz .Lfoxp_loop
	v_add_u32_e32 v97, s38, v104
	v_add_u32_e32 v100, s38, v157
	ds_read_b128 v[48:51], v97 offset:18560
	ds_read_b128 v[52:55], v97 offset:18592
	ds_read_b128 v[56:59], v97 offset:18624
	ds_read_b128 v[60:63], v97 offset:18656
	ds_read_b128 v[208:211], v100 offset:4608
	ds_read_b128 v[212:215], v100 offset:4640
	ds_read_b128 v[216:219], v100 offset:4672
	ds_read_b128 v[220:223], v100 offset:4704
	ds_read_b128 v[32:35], v97 offset:18432
	ds_read_b128 v[36:39], v97 offset:18464
	ds_read_b128 v[40:43], v97 offset:18496
	ds_read_b128 v[44:47], v97 offset:18528
	ds_read_b128 v[224:227], v100 offset:0
	ds_read_b128 v[228:231], v100 offset:32
	ds_read_b128 v[232:235], v100 offset:64
	ds_read_b128 v[236:239], v100 offset:96
	s_waitcnt lgkmcnt(11)
	v_mfma_f32_32x32x16_bf16 v[48:63], v[208:211], v[72:75], v[48:63]
	s_waitcnt lgkmcnt(10)
	v_mfma_f32_32x32x16_bf16 v[48:63], v[212:215], v[64:67], v[48:63]
	s_waitcnt lgkmcnt(9)
	v_mfma_f32_32x32x16_bf16 v[48:63], v[216:219], v[68:71], v[48:63]
	s_waitcnt lgkmcnt(8)
	v_mfma_f32_32x32x16_bf16 v[48:63], v[220:223], v[76:79], v[48:63]
	s_waitcnt lgkmcnt(3)
	v_mfma_f32_32x32x16_bf16 v[32:47], v[224:227], v[72:75], v[32:47]
	s_waitcnt lgkmcnt(2)
	v_mfma_f32_32x32x16_bf16 v[32:47], v[228:231], v[64:67], v[32:47]
	s_waitcnt lgkmcnt(1)
	v_mfma_f32_32x32x16_bf16 v[32:47], v[232:235], v[68:71], v[32:47]
	s_waitcnt lgkmcnt(0)
	v_mfma_f32_32x32x16_bf16 v[32:47], v[236:239], v[76:79], v[32:47]
	s_nop 7
	s_nop 7
.Lfoxp_loop:
	s_add_i32 s42, s10, -2
	s_max_i32 s42, s42, 0
	s_lshl_b32 s47, s42, 6
	s_mov_b32 s43, 0
	s_lshl_b64 s[42:43], s[42:43], 19
	v_lshl_add_u64 v[136:137], v[92:93], 0, s[42:43]
	v_lshl_add_u64 v[244:245], v[136:137], 0, s[34:35]
	v_lshl_add_u64 v[136:137], v[136:137], 0, s[36:37]
	global_load_dwordx4 v[80:83], v[244:245], off
	global_load_dwordx4 v[84:87], v[136:137], off
	s_and_saveexec_b64 s[48:49], s[0:1]
	s_cbranch_execz .Lfoxp_g_a
	v_add_lshl_u32 v164, s47, v138, 2
	global_load_dword v165, v164, s[30:31]
.Lfoxp_g_a:
	s_or_b64 exec, exec, s[48:49]
	s_and_b64 vcc, exec, s[4:5]
	s_cbranch_vccz .Lfoxp_w_a
	v_add_u32_e32 v97, s39, v104
	v_add_u32_e32 v100, s39, v157
	v_add_u32_e32 v102, s38, v158
	ds_read_b128 v[192:195], v97 offset:18560
	ds_read_b128 v[196:199], v97 offset:18592
	ds_read_b128 v[200:203], v97 offset:18624
	ds_read_b128 v[204:207], v97 offset:18656
	ds_read_b128 v[208:211], v100 offset:4608
	ds_read_b128 v[212:215], v100 offset:4640
	ds_read_b128 v[216:219], v100 offset:4672
	ds_read_b128 v[220:223], v100 offset:4704
	v_max3_f32 v116, v48, v49, v50
	v_max3_f32 v117, v51, v52, v53
	v_max3_f32 v118, v54, v55, v56
	v_max3_f32 v119, v57, v58, v59
	v_max3_f32 v120, v60, v61, v62
	v_max3_f32 v121, v63, v32, v33
	v_max3_f32 v122, v34, v35, v36
	v_max3_f32 v123, v37, v38, v39
	v_max3_f32 v124, v40, v41, v42
	v_max3_f32 v125, v43, v44, v45
	s_waitcnt lgkmcnt(3)
	v_mfma_f32_32x32x16_bf16 v[192:207], v[208:211], v[72:75], v[192:207]
	v_max3_f32 v116, v116, v117, v118
	v_max3_f32 v117, v119, v120, v121
	v_max3_f32 v118, v122, v123, v124
	v_max3_f32 v119, v125, v46, v47
	s_waitcnt lgkmcnt(2)
	v_mfma_f32_32x32x16_bf16 v[192:207], v[212:215], v[64:67], v[192:207]
	v_max3_f32 v116, v116, v117, v118
	v_max_f32_e32 v116, v116, v119
	ds_bpermute_b32 v113, v112, v116
	ds_read_b128 v[176:179], v97 offset:18432
	ds_read_b128 v[180:183], v97 offset:18464
	ds_read_b128 v[184:187], v97 offset:18496
	ds_read_b128 v[188:191], v97 offset:18528
	s_waitcnt lgkmcnt(6)
	v_mfma_f32_32x32x16_bf16 v[192:207], v[216:219], v[68:71], v[192:207]
	ds_read_b128 v[224:227], v100 offset:0
	ds_read_b128 v[228:231], v100 offset:32
	ds_read_b128 v[232:235], v100 offset:64
	ds_read_b128 v[236:239], v100 offset:96
	s_waitcnt lgkmcnt(9)
	v_mfma_f32_32x32x16_bf16 v[192:207], v[220:223], v[76:79], v[192:207]
	s_waitcnt lgkmcnt(8)
	v_max3_f32 v96, v94, v116, v113
	v_cmp_gt_f32_e32 vcc, v96, v94
	ds_read_b64_tr_b16 v[116:117], v102 offset:13824
	ds_read_b64_tr_b16 v[118:119], v102 offset:14976
	ds_read_b64_tr_b16 v[120:121], v102 offset:13888
	ds_read_b64_tr_b16 v[122:123], v102 offset:15040
	s_cbranch_vccz .Lfoxp_nr_a
	v_sub_f32_e32 v114, v94, v96
	v_exp_f32_e32 v114, v114
	s_nop 0
	v_pk_mul_f32 v[0:1], v[0:1], v[114:115] op_sel_hi:[1,0]
	v_pk_mul_f32 v[2:3], v[2:3], v[114:115] op_sel_hi:[1,0]
	v_pk_mul_f32 v[4:5], v[4:5], v[114:115] op_sel_hi:[1,0]
	v_pk_mul_f32 v[6:7], v[6:7], v[114:115] op_sel_hi:[1,0]
	v_pk_mul_f32 v[8:9], v[8:9], v[114:115] op_sel_hi:[1,0]
	v_pk_mul_f32 v[10:11], v[10:11], v[114:115] op_sel_hi:[1,0]
	v_pk_mul_f32 v[12:13], v[12:13], v[114:115] op_sel_hi:[1,0]
	v_pk_mul_f32 v[14:15], v[14:15], v[114:115] op_sel_hi:[1,0]
	v_pk_mul_f32 v[16:17], v[16:17], v[114:115] op_sel_hi:[1,0]
	v_pk_mul_f32 v[18:19], v[18:19], v[114:115] op_sel_hi:[1,0]
	v_pk_mul_f32 v[20:21], v[20:21], v[114:115] op_sel_hi:[1,0]
	v_pk_mul_f32 v[22:23], v[22:23], v[114:115] op_sel_hi:[1,0]
	v_pk_mul_f32 v[24:25], v[24:25], v[114:115] op_sel_hi:[1,0]
	v_pk_mul_f32 v[26:27], v[26:27], v[114:115] op_sel_hi:[1,0]
	v_pk_mul_f32 v[28:29], v[28:29], v[114:115] op_sel_hi:[1,0]
	v_pk_mul_f32 v[30:31], v[30:31], v[114:115] op_sel_hi:[1,0]
	v_pk_mul_f32 v[108:109], v[108:109], v[114:115] op_sel_hi:[1,0]
	v_pk_mul_f32 v[110:111], v[110:111], v[114:115] op_sel_hi:[1,0]
; #define LDS_AS __attribute__((address_space(3)))
; #define MFMA(a, b, c) __builtin_amdgcn_mfma_f32_32x32x16_bf16((a), (b), (c), 0, 0, 0)
; DI unsigned pk2(float a, float b) { f32x2 v = {a, b}; bf16x2v r = __builtin_convertvector(v, bf16x2v); return __builtin_bit_cast(unsigned, r); }
; DI float max3f(float a, float b, float c) { float r; asm("v_max3_f32 %0, %1, %2, %3" : "=v"(r) : "v"(a), "v"(b), "v"(c)); return r; }
; DI void fox_softmax32(f32x16& s, AttnState& st, bf16x8 (&pf)[2]) {
;     float mx = max2f(s[0], s[1]);
; #pragma unroll
;     for (int i = 2; i < 16; i += 2) mx = max3f(mx, s[i], s[i + 1]);
;     mx = max2f(mx, __shfl_xor(mx, 32));
;     const float mn = max2f(st.m, mx);
;     if (__any(mn > st.m)) { const float a = __builtin_amdgcn_exp2f(st.m - mn); st.o0 = st.o0 * a; st.o1 = st.o1 * a; st.l *= a; }
;     st.m = mn;
;     const f32x2 mn2 = {mn, mn};
;     f32x2 acc2 = {0.f, 0.f};
; #pragma unroll
;     for (int i = 0; i < 16; i += 2) {
;         f32x2 t = {s[i], s[i + 1]};
;         t = t - mn2;
;         t[0] = __builtin_amdgcn_exp2f(t[0]); t[1] = __builtin_amdgcn_exp2f(t[1]);
;         acc2 = acc2 + t;
;         s[i] = t[0]; s[i + 1] = t[1];
;     }
;     st.l += acc2[0] + acc2[1];
; #pragma unroll
;     for (int s2 = 0; s2 < 2; ++s2) {
;         u32x4 w;
;         w[0] = pk2(s[8 * s2 + 0], s[8 * s2 + 1]); w[1] = pk2(s[8 * s2 + 2], s[8 * s2 + 3]); w[2] = pk2(s[8 * s2 + 4], s[8 * s2 + 5]); w[3] = pk2(s[8 * s2 + 6], s[8 * s2 + 7]);
;         pf[s2] = __builtin_bit_cast(bf16x8, w);
;     }
; }
; DI void fox_pv32(LDS_AS const char* Vl, const bf16x8 (&pf)[2], AttnState& st, int lane) {
;     const int hh = lane >> 5, i16 = lane & 15, qq = i16 >> 2, pp = i16 & 3, gg = (lane >> 4) & 1;
; #pragma unroll
;     for (int s2 = 0; s2 < 2; ++s2)
; #pragma unroll
;         for (int dt = 0; dt < 2; ++dt) {
;             LDS_AS const char* a_lo = Vl + (16 * s2 + 4 * hh + qq) * 144 + (32 * dt + 16 * gg + 4 * pp) * 2;
;             const s16x4 lo = __builtin_amdgcn_ds_read_tr16_b64_v4i16((LDS_AS s16x4*)a_lo);
;             const s16x4 hi = __builtin_amdgcn_ds_read_tr16_b64_v4i16((LDS_AS s16x4*)(a_lo + 8 * 144));
;             const bf16x8 vf = __builtin_shufflevector(lo, hi, 0, 1, 2, 3, 4, 5, 6, 7);
;             if (dt == 0) st.o0 = MFMA(vf, pf[s2], st.o0); else st.o1 = MFMA(vf, pf[s2], st.o1);
;         }
; }
.Lfoxp_nr_a:
	v_mov_b32_e32 v94, v96
	v_pk_add_f32 v[48:49], v[48:49], v[96:97] op_sel_hi:[1,0] neg_lo:[0,1] neg_hi:[0,1]
	v_pk_add_f32 v[50:51], v[50:51], v[96:97] op_sel_hi:[1,0] neg_lo:[0,1] neg_hi:[0,1]
	v_pk_add_f32 v[52:53], v[52:53], v[96:97] op_sel_hi:[1,0] neg_lo:[0,1] neg_hi:[0,1]
	v_pk_add_f32 v[54:55], v[54:55], v[96:97] op_sel_hi:[1,0] neg_lo:[0,1] neg_hi:[0,1]
	v_pk_add_f32 v[56:57], v[56:57], v[96:97] op_sel_hi:[1,0] neg_lo:[0,1] neg_hi:[0,1]
	v_pk_add_f32 v[58:59], v[58:59], v[96:97] op_sel_hi:[1,0] neg_lo:[0,1] neg_hi:[0,1]
	v_pk_add_f32 v[60:61], v[60:61], v[96:97] op_sel_hi:[1,0] neg_lo:[0,1] neg_hi:[0,1]
	v_pk_add_f32 v[62:63], v[62:63], v[96:97] op_sel_hi:[1,0] neg_lo:[0,1] neg_hi:[0,1]
	v_exp_f32_e32 v48, v48
	v_exp_f32_e32 v49, v49
	v_exp_f32_e32 v50, v50
	v_exp_f32_e32 v51, v51
	s_waitcnt lgkmcnt(7)
	v_mfma_f32_32x32x16_bf16 v[176:191], v[224:227], v[72:75], v[176:191]
	v_exp_f32_e32 v52, v52
	v_exp_f32_e32 v53, v53
	v_exp_f32_e32 v54, v54
	v_exp_f32_e32 v55, v55
	s_waitcnt lgkmcnt(6)
	v_mfma_f32_32x32x16_bf16 v[176:191], v[228:231], v[64:67], v[176:191]
	v_exp_f32_e32 v56, v56
	v_exp_f32_e32 v57, v57
	v_exp_f32_e32 v58, v58
	v_exp_f32_e32 v59, v59
	s_waitcnt lgkmcnt(5)
	v_mfma_f32_32x32x16_bf16 v[176:191], v[232:235], v[68:71], v[176:191]
	v_exp_f32_e32 v60, v60
	v_exp_f32_e32 v61, v61
	v_exp_f32_e32 v62, v62
	v_exp_f32_e32 v63, v63
	s_waitcnt lgkmcnt(4)
	v_mfma_f32_32x32x16_bf16 v[176:191], v[236:239], v[76:79], v[176:191]
	ds_read_b64_tr_b16 v[124:125], v102 offset:16128
	ds_read_b64_tr_b16 v[126:127], v102 offset:17280
	ds_read_b64_tr_b16 v[132:133], v102 offset:16192
	ds_read_b64_tr_b16 v[134:135], v102 offset:17344
	v_pk_add_f32 v[108:109], v[108:109], v[48:49]
	v_cvt_pk_bf16_f32 v48, v48, v49
	v_pk_add_f32 v[108:109], v[108:109], v[50:51]
	v_cvt_pk_bf16_f32 v49, v50, v51
	v_pk_add_f32 v[108:109], v[108:109], v[52:53]
	v_cvt_pk_bf16_f32 v50, v52, v53
	v_pk_add_f32 v[108:109], v[108:109], v[54:55]
	v_cvt_pk_bf16_f32 v51, v54, v55
	v_pk_add_f32 v[108:109], v[108:109], v[56:57]
	v_cvt_pk_bf16_f32 v52, v56, v57
	v_pk_add_f32 v[108:109], v[108:109], v[58:59]
	v_cvt_pk_bf16_f32 v53, v58, v59
	v_pk_add_f32 v[108:109], v[108:109], v[60:61]
	v_cvt_pk_bf16_f32 v54, v60, v61
	v_pk_add_f32 v[108:109], v[108:109], v[62:63]
	v_cvt_pk_bf16_f32 v55, v62, v63
	v_pk_add_f32 v[32:33], v[32:33], v[96:97] op_sel_hi:[1,0] neg_lo:[0,1] neg_hi:[0,1]
	v_pk_add_f32 v[34:35], v[34:35], v[96:97] op_sel_hi:[1,0] neg_lo:[0,1] neg_hi:[0,1]
	v_pk_add_f32 v[36:37], v[36:37], v[96:97] op_sel_hi:[1,0] neg_lo:[0,1] neg_hi:[0,1]
	v_pk_add_f32 v[38:39], v[38:39], v[96:97] op_sel_hi:[1,0] neg_lo:[0,1] neg_hi:[0,1]
	v_pk_add_f32 v[40:41], v[40:41], v[96:97] op_sel_hi:[1,0] neg_lo:[0,1] neg_hi:[0,1]
	v_pk_add_f32 v[42:43], v[42:43], v[96:97] op_sel_hi:[1,0] neg_lo:[0,1] neg_hi:[0,1]
	v_pk_add_f32 v[44:45], v[44:45], v[96:97] op_sel_hi:[1,0] neg_lo:[0,1] neg_hi:[0,1]
	v_pk_add_f32 v[46:47], v[46:47], v[96:97] op_sel_hi:[1,0] neg_lo:[0,1] neg_hi:[0,1]
	s_nop 0
	s_waitcnt lgkmcnt(6)
	v_mfma_f32_32x32x16_bf16 v[16:31], v[116:119], v[48:51], v[16:31]
	v_exp_f32_e32 v32, v32
	v_exp_f32_e32 v33, v33
	v_exp_f32_e32 v34, v34
	v_exp_f32_e32 v35, v35
	s_waitcnt lgkmcnt(4)
	v_mfma_f32_32x32x16_bf16 v[0:15], v[120:123], v[48:51], v[0:15]
	ds_read_b64_tr_b16 v[148:149], v102 offset:9216
	ds_read_b64_tr_b16 v[150:151], v102 offset:10368
	ds_read_b64_tr_b16 v[152:153], v102 offset:9280
	ds_read_b64_tr_b16 v[154:155], v102 offset:10432
	v_exp_f32_e32 v36, v36
	v_exp_f32_e32 v37, v37
	v_exp_f32_e32 v38, v38
	v_exp_f32_e32 v39, v39
	s_waitcnt lgkmcnt(6)
	v_mfma_f32_32x32x16_bf16 v[16:31], v[124:127], v[52:55], v[16:31]
	v_exp_f32_e32 v40, v40
	v_exp_f32_e32 v41, v41
	v_exp_f32_e32 v42, v42
	v_exp_f32_e32 v43, v43
	s_waitcnt lgkmcnt(4)
	v_mfma_f32_32x32x16_bf16 v[0:15], v[132:135], v[52:55], v[0:15]
	ds_read_b64_tr_b16 v[240:241], v102 offset:11520
	ds_read_b64_tr_b16 v[242:243], v102 offset:12672
	ds_read_b64_tr_b16 v[160:161], v102 offset:11584
	ds_read_b64_tr_b16 v[162:163], v102 offset:12736
	v_exp_f32_e32 v44, v44
	v_exp_f32_e32 v45, v45
	v_exp_f32_e32 v46, v46
	v_exp_f32_e32 v47, v47
	v_pk_add_f32 v[110:111], v[110:111], v[32:33]
	v_cvt_pk_bf16_f32 v32, v32, v33
	v_pk_add_f32 v[110:111], v[110:111], v[34:35]
	v_cvt_pk_bf16_f32 v33, v34, v35
	v_pk_add_f32 v[110:111], v[110:111], v[36:37]
	v_cvt_pk_bf16_f32 v34, v36, v37
	v_pk_add_f32 v[110:111], v[110:111], v[38:39]
	v_cvt_pk_bf16_f32 v35, v38, v39
	v_pk_add_f32 v[110:111], v[110:111], v[40:41]
	v_cvt_pk_bf16_f32 v36, v40, v41
	v_pk_add_f32 v[110:111], v[110:111], v[42:43]
	v_cvt_pk_bf16_f32 v37, v42, v43
	v_pk_add_f32 v[110:111], v[110:111], v[44:45]
	v_cvt_pk_bf16_f32 v38, v44, v45
	v_pk_add_f32 v[110:111], v[110:111], v[46:47]
	v_cvt_pk_bf16_f32 v39, v46, v47
	s_nop 1
	s_waitcnt lgkmcnt(6)
	v_mfma_f32_32x32x16_bf16 v[16:31], v[148:151], v[32:35], v[16:31]
	s_waitcnt lgkmcnt(4)
	v_mfma_f32_32x32x16_bf16 v[0:15], v[152:155], v[32:35], v[0:15]
	s_waitcnt lgkmcnt(2)
	v_mfma_f32_32x32x16_bf16 v[16:31], v[240:243], v[36:39], v[16:31]
	s_waitcnt lgkmcnt(0)
	v_mfma_f32_32x32x16_bf16 v[0:15], v[160:163], v[36:39], v[0:15]
.Lfoxp_w_a:
	s_waitcnt vmcnt(0)
	v_add_u32_e32 v164, s46, v159
	ds_write_b128 v164, v[80:83]
	ds_write_b128 v164, v[84:87] offset:9216
	s_and_saveexec_b64 s[48:49], s[0:1]
	s_cbranch_execz .Lfoxp_ws_a
	v_sub_f32_e32 v165, v95, v165
	v_add_u32_e32 v164, s46, v99
	ds_write_b32 v164, v165 offset:18432
; #define LDS_AS __attribute__((address_space(3)))
; DI void fox_softmax32(f32x16& s, AttnState& st, bf16x8 (&pf)[2]) {
;     float mx = max2f(s[0], s[1]);
; #pragma unroll
;     for (int i = 2; i < 16; i += 2) mx = max3f(mx, s[i], s[i + 1]);
;     mx = max2f(mx, __shfl_xor(mx, 32));
;     const float mn = max2f(st.m, mx);
;     if (__any(mn > st.m)) { const float a = __builtin_amdgcn_exp2f(st.m - mn); st.o0 = st.o0 * a; st.o1 = st.o1 * a; st.l *= a; }
;     st.m = mn;
;     const f32x2 mn2 = {mn, mn};
;     f32x2 acc2 = {0.f, 0.f};
; #pragma unroll
;     for (int i = 0; i < 16; i += 2) {
;         f32x2 t = {s[i], s[i + 1]};
;         t = t - mn2;
;         t[0] = __builtin_amdgcn_exp2f(t[0]); t[1] = __builtin_amdgcn_exp2f(t[1]);
;         acc2 = acc2 + t;
;         s[i] = t[0]; s[i + 1] = t[1];
;     }
;     st.l += acc2[0] + acc2[1];
; #pragma unroll
;     for (int s2 = 0; s2 < 2; ++s2) {
;         u32x4 w;
; DI void attn_tile64_fox(LDS_AS const char* Kl, LDS_AS const char* Vl, LDS_AS const char* biasl, const bf16x8 (&q)[4], AttnState& st, int lane) {
;     const int l31 = lane & 31, hh = lane >> 5;
;     f32x16 s0, s1;
; #pragma unroll
;     for (int g = 0; g < 4; ++g) {
;         const f32x4 b0 = *(LDS_AS const f32x4*)(biasl + (8 * g + 4 * hh) * 4);
;         const f32x4 b1 = *(LDS_AS const f32x4*)(biasl + 128 + (8 * g + 4 * hh) * 4);
;         s0[4 * g] = b0[0]; s0[4 * g + 1] = b0[1]; s0[4 * g + 2] = b0[2]; s0[4 * g + 3] = b0[3];
;         s1[4 * g] = b1[0]; s1[4 * g + 1] = b1[1]; s1[4 * g + 2] = b1[2]; s1[4 * g + 3] = b1[3];
;     }
;     bf16x8 k0[4], k1[4];
; #pragma unroll
;     for (int stp = 0; stp < 4; ++stp) {
;         k1[stp] = *(LDS_AS const bf16x8*)(Kl + 32 * 144 + l31 * 144 + (2 * stp + hh) * 16);
;         k0[stp] = *(LDS_AS const bf16x8*)(Kl + l31 * 144 + (2 * stp + hh) * 16);
;     }
; #pragma unroll
;     for (int stp = 0; stp < 4; ++stp) s1 = MFMA(k1[stp], q[stp], s1);
; #pragma unroll
;     for (int stp = 0; stp < 4; ++stp) s0 = MFMA(k0[stp], q[stp], s0);
;     __builtin_amdgcn_sched_barrier(0);
;     bf16x8 pf1[2], pf0[2];
;     fox_softmax32(s1, st, pf1);
;     __builtin_amdgcn_sched_barrier(0);
;     fox_pv32(Vl + 32 * 144, pf1, st, lane);
;     __builtin_amdgcn_sched_barrier(0);
;     fox_softmax32(s0, st, pf0);
;     __builtin_amdgcn_sched_barrier(0);
;     fox_pv32(Vl, pf0, st, lane);
; }
.Lfoxp_ws_a:
	s_or_b64 exec, exec, s[48:49]
	s_mov_b32 s47, s38
	s_mov_b32 s38, s39
	s_mov_b32 s39, s46
	s_mov_b32 s46, s47
	s_add_i32 s10, s10, -1
	s_waitcnt lgkmcnt(0)
	s_barrier
	s_add_i32 s42, s10, -2
	s_max_i32 s42, s42, 0
	s_lshl_b32 s47, s42, 6
	s_mov_b32 s43, 0
	s_lshl_b64 s[42:43], s[42:43], 19
	v_lshl_add_u64 v[136:137], v[92:93], 0, s[42:43]
	v_lshl_add_u64 v[244:245], v[136:137], 0, s[34:35]
	v_lshl_add_u64 v[136:137], v[136:137], 0, s[36:37]
	global_load_dwordx4 v[80:83], v[244:245], off
	global_load_dwordx4 v[84:87], v[136:137], off
	s_and_saveexec_b64 s[48:49], s[0:1]
	s_cbranch_execz .Lfoxp_g_b
	v_add_lshl_u32 v164, s47, v138, 2
	global_load_dword v165, v164, s[30:31]
.Lfoxp_g_b:
	s_or_b64 exec, exec, s[48:49]
	s_and_b64 vcc, exec, s[4:5]
	s_cbranch_vccz .Lfoxp_w_b
	v_add_u32_e32 v97, s39, v104
	v_add_u32_e32 v100, s39, v157
	v_add_u32_e32 v102, s38, v158
	ds_read_b128 v[48:51], v97 offset:18560
	ds_read_b128 v[52:55], v97 offset:18592
	ds_read_b128 v[56:59], v97 offset:18624
	ds_read_b128 v[60:63], v97 offset:18656
	ds_read_b128 v[208:211], v100 offset:4608
	ds_read_b128 v[212:215], v100 offset:4640
	ds_read_b128 v[216:219], v100 offset:4672
	ds_read_b128 v[220:223], v100 offset:4704
	v_max3_f32 v116, v192, v193, v194
	v_max3_f32 v117, v195, v196, v197
	v_max3_f32 v118, v198, v199, v200
	v_max3_f32 v119, v201, v202, v203
	v_max3_f32 v120, v204, v205, v206
	v_max3_f32 v121, v207, v176, v177
	v_max3_f32 v122, v178, v179, v180
	v_max3_f32 v123, v181, v182, v183
	v_max3_f32 v124, v184, v185, v186
	v_max3_f32 v125, v187, v188, v189
	s_waitcnt lgkmcnt(3)
	v_mfma_f32_32x32x16_bf16 v[48:63], v[208:211], v[72:75], v[48:63]
	v_max3_f32 v116, v116, v117, v118
	v_max3_f32 v117, v119, v120, v121
	v_max3_f32 v118, v122, v123, v124
	v_max3_f32 v119, v125, v190, v191
	s_waitcnt lgkmcnt(2)
	v_mfma_f32_32x32x16_bf16 v[48:63], v[212:215], v[64:67], v[48:63]
	v_max3_f32 v116, v116, v117, v118
	v_max_f32_e32 v116, v116, v119
	ds_bpermute_b32 v113, v112, v116
	ds_read_b128 v[32:35], v97 offset:18432
	ds_read_b128 v[36:39], v97 offset:18464
	ds_read_b128 v[40:43], v97 offset:18496
	ds_read_b128 v[44:47], v97 offset:18528
	s_waitcnt lgkmcnt(6)
	v_mfma_f32_32x32x16_bf16 v[48:63], v[216:219], v[68:71], v[48:63]
	ds_read_b128 v[224:227], v100 offset:0
	ds_read_b128 v[228:231], v100 offset:32
	ds_read_b128 v[232:235], v100 offset:64
	ds_read_b128 v[236:239], v100 offset:96
	s_waitcnt lgkmcnt(9)
	v_mfma_f32_32x32x16_bf16 v[48:63], v[220:223], v[76:79], v[48:63]
	s_waitcnt lgkmcnt(8)
	v_max3_f32 v96, v94, v116, v113
	v_cmp_gt_f32_e32 vcc, v96, v94
	ds_read_b64_tr_b16 v[116:117], v102 offset:13824
	ds_read_b64_tr_b16 v[118:119], v102 offset:14976
	ds_read_b64_tr_b16 v[120:121], v102 offset:13888
	ds_read_b64_tr_b16 v[122:123], v102 offset:15040
	s_cbranch_vccz .Lfoxp_nr_b
	v_sub_f32_e32 v114, v94, v96
	v_exp_f32_e32 v114, v114
	s_nop 0
	v_pk_mul_f32 v[0:1], v[0:1], v[114:115] op_sel_hi:[1,0]
	v_pk_mul_f32 v[2:3], v[2:3], v[114:115] op_sel_hi:[1,0]
	v_pk_mul_f32 v[4:5], v[4:5], v[114:115] op_sel_hi:[1,0]
	v_pk_mul_f32 v[6:7], v[6:7], v[114:115] op_sel_hi:[1,0]
	v_pk_mul_f32 v[8:9], v[8:9], v[114:115] op_sel_hi:[1,0]
	v_pk_mul_f32 v[10:11], v[10:11], v[114:115] op_sel_hi:[1,0]
	v_pk_mul_f32 v[12:13], v[12:13], v[114:115] op_sel_hi:[1,0]
	v_pk_mul_f32 v[14:15], v[14:15], v[114:115] op_sel_hi:[1,0]
	v_pk_mul_f32 v[16:17], v[16:17], v[114:115] op_sel_hi:[1,0]
	v_pk_mul_f32 v[18:19], v[18:19], v[114:115] op_sel_hi:[1,0]
	v_pk_mul_f32 v[20:21], v[20:21], v[114:115] op_sel_hi:[1,0]
	v_pk_mul_f32 v[22:23], v[22:23], v[114:115] op_sel_hi:[1,0]
	v_pk_mul_f32 v[24:25], v[24:25], v[114:115] op_sel_hi:[1,0]
	v_pk_mul_f32 v[26:27], v[26:27], v[114:115] op_sel_hi:[1,0]
	v_pk_mul_f32 v[28:29], v[28:29], v[114:115] op_sel_hi:[1,0]
	v_pk_mul_f32 v[30:31], v[30:31], v[114:115] op_sel_hi:[1,0]
	v_pk_mul_f32 v[108:109], v[108:109], v[114:115] op_sel_hi:[1,0]
	v_pk_mul_f32 v[110:111], v[110:111], v[114:115] op_sel_hi:[1,0]
; #define LDS_AS __attribute__((address_space(3)))
; #define MFMA(a, b, c) __builtin_amdgcn_mfma_f32_32x32x16_bf16((a), (b), (c), 0, 0, 0)
; DI unsigned pk2(float a, float b) { f32x2 v = {a, b}; bf16x2v r = __builtin_convertvector(v, bf16x2v); return __builtin_bit_cast(unsigned, r); }
; DI float max3f(float a, float b, float c) { float r; asm("v_max3_f32 %0, %1, %2, %3" : "=v"(r) : "v"(a), "v"(b), "v"(c)); return r; }
; DI void fox_softmax32(f32x16& s, AttnState& st, bf16x8 (&pf)[2]) {
;     float mx = max2f(s[0], s[1]);
; #pragma unroll
;     for (int i = 2; i < 16; i += 2) mx = max3f(mx, s[i], s[i + 1]);
;     mx = max2f(mx, __shfl_xor(mx, 32));
;     const float mn = max2f(st.m, mx);
;     if (__any(mn > st.m)) { const float a = __builtin_amdgcn_exp2f(st.m - mn); st.o0 = st.o0 * a; st.o1 = st.o1 * a; st.l *= a; }
;     st.m = mn;
;     const f32x2 mn2 = {mn, mn};
;     f32x2 acc2 = {0.f, 0.f};
; #pragma unroll
;     for (int i = 0; i < 16; i += 2) {
;         f32x2 t = {s[i], s[i + 1]};
;         t = t - mn2;
;         t[0] = __builtin_amdgcn_exp2f(t[0]); t[1] = __builtin_amdgcn_exp2f(t[1]);
;         acc2 = acc2 + t;
;         s[i] = t[0]; s[i + 1] = t[1];
;     }
;     st.l += acc2[0] + acc2[1];
; #pragma unroll
;     for (int s2 = 0; s2 < 2; ++s2) {
;         u32x4 w;
;         w[0] = pk2(s[8 * s2 + 0], s[8 * s2 + 1]); w[1] = pk2(s[8 * s2 + 2], s[8 * s2 + 3]); w[2] = pk2(s[8 * s2 + 4], s[8 * s2 + 5]); w[3] = pk2(s[8 * s2 + 6], s[8 * s2 + 7]);
;         pf[s2] = __builtin_bit_cast(bf16x8, w);
;     }
; }
; DI void fox_pv32(LDS_AS const char* Vl, const bf16x8 (&pf)[2], AttnState& st, int lane) {
;     const int hh = lane >> 5, i16 = lane & 15, qq = i16 >> 2, pp = i16 & 3, gg = (lane >> 4) & 1;
; #pragma unroll
;     for (int s2 = 0; s2 < 2; ++s2)
; #pragma unroll
;         for (int dt = 0; dt < 2; ++dt) {
;             LDS_AS const char* a_lo = Vl + (16 * s2 + 4 * hh + qq) * 144 + (32 * dt + 16 * gg + 4 * pp) * 2;
;             const s16x4 lo = __builtin_amdgcn_ds_read_tr16_b64_v4i16((LDS_AS s16x4*)a_lo);
;             const s16x4 hi = __builtin_amdgcn_ds_read_tr16_b64_v4i16((LDS_AS s16x4*)(a_lo + 8 * 144));
;             const bf16x8 vf = __builtin_shufflevector(lo, hi, 0, 1, 2, 3, 4, 5, 6, 7);
;             if (dt == 0) st.o0 = MFMA(vf, pf[s2], st.o0); else st.o1 = MFMA(vf, pf[s2], st.o1);
;         }
; }
.Lfoxp_nr_b:
	v_mov_b32_e32 v94, v96
	v_pk_add_f32 v[192:193], v[192:193], v[96:97] op_sel_hi:[1,0] neg_lo:[0,1] neg_hi:[0,1]
	v_pk_add_f32 v[194:195], v[194:195], v[96:97] op_sel_hi:[1,0] neg_lo:[0,1] neg_hi:[0,1]
	v_pk_add_f32 v[196:197], v[196:197], v[96:97] op_sel_hi:[1,0] neg_lo:[0,1] neg_hi:[0,1]
	v_pk_add_f32 v[198:199], v[198:199], v[96:97] op_sel_hi:[1,0] neg_lo:[0,1] neg_hi:[0,1]
	v_pk_add_f32 v[200:201], v[200:201], v[96:97] op_sel_hi:[1,0] neg_lo:[0,1] neg_hi:[0,1]
	v_pk_add_f32 v[202:203], v[202:203], v[96:97] op_sel_hi:[1,0] neg_lo:[0,1] neg_hi:[0,1]
	v_pk_add_f32 v[204:205], v[204:205], v[96:97] op_sel_hi:[1,0] neg_lo:[0,1] neg_hi:[0,1]
	v_pk_add_f32 v[206:207], v[206:207], v[96:97] op_sel_hi:[1,0] neg_lo:[0,1] neg_hi:[0,1]
	v_exp_f32_e32 v192, v192
	v_exp_f32_e32 v193, v193
	v_exp_f32_e32 v194, v194
	v_exp_f32_e32 v195, v195
	s_waitcnt lgkmcnt(7)
	v_mfma_f32_32x32x16_bf16 v[32:47], v[224:227], v[72:75], v[32:47]
	v_exp_f32_e32 v196, v196
	v_exp_f32_e32 v197, v197
	v_exp_f32_e32 v198, v198
	v_exp_f32_e32 v199, v199
	s_waitcnt lgkmcnt(6)
	v_mfma_f32_32x32x16_bf16 v[32:47], v[228:231], v[64:67], v[32:47]
	v_exp_f32_e32 v200, v200
	v_exp_f32_e32 v201, v201
	v_exp_f32_e32 v202, v202
	v_exp_f32_e32 v203, v203
	s_waitcnt lgkmcnt(5)
	v_mfma_f32_32x32x16_bf16 v[32:47], v[232:235], v[68:71], v[32:47]
	v_exp_f32_e32 v204, v204
	v_exp_f32_e32 v205, v205
	v_exp_f32_e32 v206, v206
	v_exp_f32_e32 v207, v207
	s_waitcnt lgkmcnt(4)
	v_mfma_f32_32x32x16_bf16 v[32:47], v[236:239], v[76:79], v[32:47]
	ds_read_b64_tr_b16 v[124:125], v102 offset:16128
	ds_read_b64_tr_b16 v[126:127], v102 offset:17280
	ds_read_b64_tr_b16 v[132:133], v102 offset:16192
	ds_read_b64_tr_b16 v[134:135], v102 offset:17344
	v_pk_add_f32 v[108:109], v[108:109], v[192:193]
	v_cvt_pk_bf16_f32 v192, v192, v193
	v_pk_add_f32 v[108:109], v[108:109], v[194:195]
	v_cvt_pk_bf16_f32 v193, v194, v195
	v_pk_add_f32 v[108:109], v[108:109], v[196:197]
	v_cvt_pk_bf16_f32 v194, v196, v197
	v_pk_add_f32 v[108:109], v[108:109], v[198:199]
	v_cvt_pk_bf16_f32 v195, v198, v199
	v_pk_add_f32 v[108:109], v[108:109], v[200:201]
	v_cvt_pk_bf16_f32 v196, v200, v201
	v_pk_add_f32 v[108:109], v[108:109], v[202:203]
	v_cvt_pk_bf16_f32 v197, v202, v203
	v_pk_add_f32 v[108:109], v[108:109], v[204:205]
	v_cvt_pk_bf16_f32 v198, v204, v205
	v_pk_add_f32 v[108:109], v[108:109], v[206:207]
	v_cvt_pk_bf16_f32 v199, v206, v207
	v_pk_add_f32 v[176:177], v[176:177], v[96:97] op_sel_hi:[1,0] neg_lo:[0,1] neg_hi:[0,1]
	v_pk_add_f32 v[178:179], v[178:179], v[96:97] op_sel_hi:[1,0] neg_lo:[0,1] neg_hi:[0,1]
	v_pk_add_f32 v[180:181], v[180:181], v[96:97] op_sel_hi:[1,0] neg_lo:[0,1] neg_hi:[0,1]
	v_pk_add_f32 v[182:183], v[182:183], v[96:97] op_sel_hi:[1,0] neg_lo:[0,1] neg_hi:[0,1]
	v_pk_add_f32 v[184:185], v[184:185], v[96:97] op_sel_hi:[1,0] neg_lo:[0,1] neg_hi:[0,1]
	v_pk_add_f32 v[186:187], v[186:187], v[96:97] op_sel_hi:[1,0] neg_lo:[0,1] neg_hi:[0,1]
	v_pk_add_f32 v[188:189], v[188:189], v[96:97] op_sel_hi:[1,0] neg_lo:[0,1] neg_hi:[0,1]
	v_pk_add_f32 v[190:191], v[190:191], v[96:97] op_sel_hi:[1,0] neg_lo:[0,1] neg_hi:[0,1]
	s_nop 0
	s_waitcnt lgkmcnt(6)
	v_mfma_f32_32x32x16_bf16 v[16:31], v[116:119], v[192:195], v[16:31]
	v_exp_f32_e32 v176, v176
	v_exp_f32_e32 v177, v177
	v_exp_f32_e32 v178, v178
	v_exp_f32_e32 v179, v179
	s_waitcnt lgkmcnt(4)
	v_mfma_f32_32x32x16_bf16 v[0:15], v[120:123], v[192:195], v[0:15]
	ds_read_b64_tr_b16 v[148:149], v102 offset:9216
	ds_read_b64_tr_b16 v[150:151], v102 offset:10368
	ds_read_b64_tr_b16 v[152:153], v102 offset:9280
	ds_read_b64_tr_b16 v[154:155], v102 offset:10432
	v_exp_f32_e32 v180, v180
	v_exp_f32_e32 v181, v181
	v_exp_f32_e32 v182, v182
	v_exp_f32_e32 v183, v183
	s_waitcnt lgkmcnt(6)
	v_mfma_f32_32x32x16_bf16 v[16:31], v[124:127], v[196:199], v[16:31]
	v_exp_f32_e32 v184, v184
	v_exp_f32_e32 v185, v185
	v_exp_f32_e32 v186, v186
	v_exp_f32_e32 v187, v187
	s_waitcnt lgkmcnt(4)
	v_mfma_f32_32x32x16_bf16 v[0:15], v[132:135], v[196:199], v[0:15]
	ds_read_b64_tr_b16 v[240:241], v102 offset:11520
	ds_read_b64_tr_b16 v[242:243], v102 offset:12672
	ds_read_b64_tr_b16 v[160:161], v102 offset:11584
	ds_read_b64_tr_b16 v[162:163], v102 offset:12736
	v_exp_f32_e32 v188, v188
	v_exp_f32_e32 v189, v189
	v_exp_f32_e32 v190, v190
	v_exp_f32_e32 v191, v191
	v_pk_add_f32 v[110:111], v[110:111], v[176:177]
	v_cvt_pk_bf16_f32 v176, v176, v177
	v_pk_add_f32 v[110:111], v[110:111], v[178:179]
	v_cvt_pk_bf16_f32 v177, v178, v179
	v_pk_add_f32 v[110:111], v[110:111], v[180:181]
	v_cvt_pk_bf16_f32 v178, v180, v181
	v_pk_add_f32 v[110:111], v[110:111], v[182:183]
	v_cvt_pk_bf16_f32 v179, v182, v183
	v_pk_add_f32 v[110:111], v[110:111], v[184:185]
	v_cvt_pk_bf16_f32 v180, v184, v185
	v_pk_add_f32 v[110:111], v[110:111], v[186:187]
	v_cvt_pk_bf16_f32 v181, v186, v187
	v_pk_add_f32 v[110:111], v[110:111], v[188:189]
	v_cvt_pk_bf16_f32 v182, v188, v189
	v_pk_add_f32 v[110:111], v[110:111], v[190:191]
	v_cvt_pk_bf16_f32 v183, v190, v191
	s_nop 1
	s_waitcnt lgkmcnt(6)
	v_mfma_f32_32x32x16_bf16 v[16:31], v[148:151], v[176:179], v[16:31]
	s_waitcnt lgkmcnt(4)
	v_mfma_f32_32x32x16_bf16 v[0:15], v[152:155], v[176:179], v[0:15]
	s_waitcnt lgkmcnt(2)
	v_mfma_f32_32x32x16_bf16 v[16:31], v[240:243], v[180:183], v[16:31]
	s_waitcnt lgkmcnt(0)
	v_mfma_f32_32x32x16_bf16 v[0:15], v[160:163], v[180:183], v[0:15]

; #define LDS_AS __attribute__((address_space(3)))
; template <int MODE>
; DI void prompt_unit(const Params& p, int b, int h, int qt, char* smem) {
;     ...
;         if (kt > 0) pload(kt - 1);
;         if (!wdone) {
;             LDS_AS const char* sb = lb + stg * PSTG;
;             if (MODE == 1 && kt * 64 + 63 < wq0) attn_tile64_fox(sb, sb + 9216, sb + 18432, q, st, lane);
;             else
; #pragma unroll
;     ...
;                 const int kp0 = kt * 64 + sub * 32;
;                 if (kp0 <= wq0 + 31) {
;                     const bool nm = (kp0 + 31 >= wq0);
;                     attn_subtile<MODE>(sb + sub * 32 * 144, sb + 9216 + sub * 32 * 144, sb + 18432 + sub * 128, q, st, kp0, qpos, nm, lane);
;                 }
;             }
;             if (MODE == 0) wdone = __all(st.l < -SB_THRESH);
;         }
;         if (kt > 0) pstore(stg ^ 1);
;         if (MODE == 0) { if (__syncthreads_and(wdone ? 1 : 0)) break; }
;         else __syncthreads();
;         stg ^= 1;
;     }
;     if (MODE == 1) { const float lt = st.l + __shfl_xor(st.l, 32); const float inv = 1.0f / lt; st.o0 = st.o0 * inv; st.o1 = st.o1 * inv; }
.Lfoxp_ws_b:
	s_or_b64 exec, exec, s[48:49]
	s_mov_b32 s47, s38
	s_mov_b32 s38, s39
	s_mov_b32 s39, s46
	s_mov_b32 s46, s47
	s_add_i32 s10, s10, -1
	s_waitcnt lgkmcnt(0)
	s_barrier
	s_cmp_ge_i32 s10, 0
	s_cbranch_scc1 .Lfoxp_loop
	v_add_f32_e32 v108, v108, v109
	v_add_f32_e32 v110, v110, v111
	v_add_f32_e32 v107, v108, v110
	s_branch .LBB0_548
